# P3 rstd_prefetch rewritten: all six unit slots' partial-sum loads issued together (one memory round trip instead of six)
# speedup vs baseline: 1.0017x; 1.0017x over previous
; #define LAS __attribute__((address_space(3)))
; __device__ __forceinline__ void rstd_prefetch(const Frame& F, const float* PP, const float* PS) {
;     LAS int* PMT = (LAS int*)(F.lds + PMT_OFF); LAS float* RSL = (LAS float*)(F.lds + RSL_OFF);
;     for (int i = 0; i < RSL_SLOTS; ++i) { const int L = i * F.G + (int)blockIdx.x; const bool ok = (L < 1496) && (F.G % 8 == 0);
;         const int pm = ok ? unit_pm_n5632(L) : -1;
;         if (ok && F.tid < 256) RSL[i * 256 + F.tid] = pg8::row_rstd(PP, PS, pm * 256 + F.tid);
;         if (F.tid == 0) PMT[i] = pm; }
.LBB0_508:
	s_cmpk_lt_i32 s2, 0x5d8
	s_cselect_b64 s[12:13], -1, 0
	s_add_u32 s16, s22, 0xfd80000
	s_addc_u32 s17, s23, 0
	s_add_u32 s36, s22, 0xfdc0000
	s_addc_u32 s37, s23, 0
	s_mov_b32 s3, s2
	s_mov_b32 s6, -1
	s_cmpk_lt_i32 s3, 0x5d8
	s_cbranch_scc0 .Lrs_p3_n0
	s_cmp_eq_u64 s[90:91], 0
	s_cbranch_scc1 .Lrs_p3_n0
	s_and_b32 s14, s3, 7
	s_mul_i32 s14, s14, 0xbb
	s_lshr_b32 s15, s3, 3
	s_add_i32 s14, s14, s15
	s_mul_hi_u32 s15, s14, 0x1745d18
	s_mul_i32 s19, s15, 0xb0
	s_sub_i32 s14, s14, s19
	s_lshl_b32 s15, s15, 3
	s_sub_i32 s19, 0x44, s15
	s_min_i32 s19, s19, 8
	s_sub_i32 s19, s19, 1
	s_and_b32 s14, s14, s19
	s_add_i32 s6, s15, s14
.Lrs_p3_n0:
	s_add_i32 s3, s3, s18
	s_mov_b32 s7, -1
	s_cmpk_lt_i32 s3, 0x5d8
	s_cbranch_scc0 .Lrs_p3_n1
	s_cmp_eq_u64 s[90:91], 0
	s_cbranch_scc1 .Lrs_p3_n1
	s_and_b32 s14, s3, 7
	s_mul_i32 s14, s14, 0xbb
	s_lshr_b32 s15, s3, 3
	s_add_i32 s14, s14, s15
	s_mul_hi_u32 s15, s14, 0x1745d18
	s_mul_i32 s19, s15, 0xb0
	s_sub_i32 s14, s14, s19
	s_lshl_b32 s15, s15, 3
	s_sub_i32 s19, 0x44, s15
	s_min_i32 s19, s19, 8
	s_sub_i32 s19, s19, 1
	s_and_b32 s14, s14, s19
	s_add_i32 s7, s15, s14
.Lrs_p3_n1:
	s_add_i32 s3, s3, s18
	s_mov_b32 s8, -1
	s_cmpk_lt_i32 s3, 0x5d8
	s_cbranch_scc0 .Lrs_p3_n2
	s_cmp_eq_u64 s[90:91], 0
	s_cbranch_scc1 .Lrs_p3_n2
	s_and_b32 s14, s3, 7
	s_mul_i32 s14, s14, 0xbb
	s_lshr_b32 s15, s3, 3
	s_add_i32 s14, s14, s15
	s_mul_hi_u32 s15, s14, 0x1745d18
	s_mul_i32 s19, s15, 0xb0
	s_sub_i32 s14, s14, s19
	s_lshl_b32 s15, s15, 3
	s_sub_i32 s19, 0x44, s15
	s_min_i32 s19, s19, 8
	s_sub_i32 s19, s19, 1
	s_and_b32 s14, s14, s19
	s_add_i32 s8, s15, s14
.Lrs_p3_n2:
	s_add_i32 s3, s3, s18
	s_mov_b32 s9, -1
	s_cmpk_lt_i32 s3, 0x5d8
	s_cbranch_scc0 .Lrs_p3_n3
	s_cmp_eq_u64 s[90:91], 0
	s_cbranch_scc1 .Lrs_p3_n3
	s_and_b32 s14, s3, 7
	s_mul_i32 s14, s14, 0xbb
	s_lshr_b32 s15, s3, 3
	s_add_i32 s14, s14, s15
	s_mul_hi_u32 s15, s14, 0x1745d18
	s_mul_i32 s19, s15, 0xb0
	s_sub_i32 s14, s14, s19
	s_lshl_b32 s15, s15, 3
	s_sub_i32 s19, 0x44, s15
	s_min_i32 s19, s19, 8
	s_sub_i32 s19, s19, 1
	s_and_b32 s14, s14, s19
	s_add_i32 s9, s15, s14
.Lrs_p3_n3:
	s_add_i32 s3, s3, s18
	s_mov_b32 s10, -1
	s_cmpk_lt_i32 s3, 0x5d8
	s_cbranch_scc0 .Lrs_p3_n4
	s_cmp_eq_u64 s[90:91], 0
	s_cbranch_scc1 .Lrs_p3_n4
	s_and_b32 s14, s3, 7
	s_mul_i32 s14, s14, 0xbb
	s_lshr_b32 s15, s3, 3
	s_add_i32 s14, s14, s15
	s_mul_hi_u32 s15, s14, 0x1745d18
	s_mul_i32 s19, s15, 0xb0
	s_sub_i32 s14, s14, s19
	s_lshl_b32 s15, s15, 3
	s_sub_i32 s19, 0x44, s15
	s_min_i32 s19, s19, 8
	s_sub_i32 s19, s19, 1
	s_and_b32 s14, s14, s19
	s_add_i32 s10, s15, s14
.Lrs_p3_n4:
	s_add_i32 s3, s3, s18
	s_mov_b32 s11, -1
	s_cmpk_lt_i32 s3, 0x5d8
	s_cbranch_scc0 .Lrs_p3_n5
	s_cmp_eq_u64 s[90:91], 0
	s_cbranch_scc1 .Lrs_p3_n5
	s_and_b32 s14, s3, 7
	s_mul_i32 s14, s14, 0xbb
	s_lshr_b32 s15, s3, 3
	s_add_i32 s14, s14, s15
	s_mul_hi_u32 s15, s14, 0x1745d18
	s_mul_i32 s19, s15, 0xb0
	s_sub_i32 s14, s14, s19
	s_lshl_b32 s15, s15, 3
	s_sub_i32 s19, 0x44, s15
	s_min_i32 s19, s19, 8
	s_sub_i32 s19, s19, 1
	s_and_b32 s14, s14, s19
	s_add_i32 s11, s15, s14
.Lrs_p3_n5:
	s_add_i32 s3, s3, s18
	v_cmp_gt_u32_e32 vcc, 0x100, v188
	s_and_saveexec_b64 s[34:35], vcc
	s_cbranch_execz .Lrs_p3_rows_done
	s_cmp_lt_i32 s6, 0
	s_cbranch_scc1 .Lrs_p3_l0
	s_cmp_lt_i32 s6, 64
	s_cbranch_scc0 .Lrs_p3_s0
	v_lshl_add_u32 v1, s6, 8, v188
	v_lshlrev_b32_e32 v1, 4, v1
	global_load_dwordx4 v[20:23], v1, s[16:17]
	s_branch .Lrs_p3_l0
.Lrs_p3_s0:
	s_sub_i32 s14, s6, 64
	v_lshl_add_u32 v1, s14, 8, v188
	v_lshlrev_b32_e32 v1, 6, v1
	global_load_dwordx4 v[20:23], v1, s[36:37]
	global_load_dwordx4 v[24:27], v1, s[36:37] offset:16
	global_load_dwordx4 v[28:31], v1, s[36:37] offset:32
	global_load_dwordx4 v[32:35], v1, s[36:37] offset:48
.Lrs_p3_l0:
	s_cmp_lt_i32 s7, 0
	s_cbranch_scc1 .Lrs_p3_l1
	s_cmp_lt_i32 s7, 64
	s_cbranch_scc0 .Lrs_p3_s1
	v_lshl_add_u32 v1, s7, 8, v188
	v_lshlrev_b32_e32 v1, 4, v1
	global_load_dwordx4 v[36:39], v1, s[16:17]
	s_branch .Lrs_p3_l1
.Lrs_p3_s1:
	s_sub_i32 s14, s7, 64
	v_lshl_add_u32 v1, s14, 8, v188
	v_lshlrev_b32_e32 v1, 6, v1
	global_load_dwordx4 v[36:39], v1, s[36:37]
	global_load_dwordx4 v[40:43], v1, s[36:37] offset:16
	global_load_dwordx4 v[44:47], v1, s[36:37] offset:32
	global_load_dwordx4 v[48:51], v1, s[36:37] offset:48
.Lrs_p3_l1:
	s_cmp_lt_i32 s8, 0
	s_cbranch_scc1 .Lrs_p3_l2
	s_cmp_lt_i32 s8, 64
	s_cbranch_scc0 .Lrs_p3_s2
	v_lshl_add_u32 v1, s8, 8, v188
	v_lshlrev_b32_e32 v1, 4, v1
	global_load_dwordx4 v[52:55], v1, s[16:17]
	s_branch .Lrs_p3_l2
.Lrs_p3_s2:
	s_sub_i32 s14, s8, 64
	v_lshl_add_u32 v1, s14, 8, v188
	v_lshlrev_b32_e32 v1, 6, v1
	global_load_dwordx4 v[52:55], v1, s[36:37]
	global_load_dwordx4 v[56:59], v1, s[36:37] offset:16
	global_load_dwordx4 v[60:63], v1, s[36:37] offset:32
	global_load_dwordx4 v[64:67], v1, s[36:37] offset:48
.Lrs_p3_l2:
	s_cmp_lt_i32 s9, 0
	s_cbranch_scc1 .Lrs_p3_l3
	s_cmp_lt_i32 s9, 64
	s_cbranch_scc0 .Lrs_p3_s3
	v_lshl_add_u32 v1, s9, 8, v188
	v_lshlrev_b32_e32 v1, 4, v1
	global_load_dwordx4 v[68:71], v1, s[16:17]
	s_branch .Lrs_p3_l3
.Lrs_p3_s3:
	s_sub_i32 s14, s9, 64
	v_lshl_add_u32 v1, s14, 8, v188
	v_lshlrev_b32_e32 v1, 6, v1
	global_load_dwordx4 v[68:71], v1, s[36:37]
	global_load_dwordx4 v[72:75], v1, s[36:37] offset:16
	global_load_dwordx4 v[76:79], v1, s[36:37] offset:32
	global_load_dwordx4 v[80:83], v1, s[36:37] offset:48
.Lrs_p3_l3:
	s_cmp_lt_i32 s10, 0
	s_cbranch_scc1 .Lrs_p3_l4
	s_cmp_lt_i32 s10, 64
	s_cbranch_scc0 .Lrs_p3_s4
	v_lshl_add_u32 v1, s10, 8, v188
	v_lshlrev_b32_e32 v1, 4, v1
	global_load_dwordx4 v[84:87], v1, s[16:17]
	s_branch .Lrs_p3_l4
; __device__ __forceinline__ float row_rstd(const float* PP, const float* PS, int row) {
;     float ss;
;     if (row < TP) { const f32x4 a = NTL((const f32x4*)(PP + (size_t)row * 4)); ss = (a[0] + a[1]) + (a[2] + a[3]); }
;     else { const f32x4* p = (const f32x4*)(PS + (size_t)(row - TP) * 16); const f32x4 a = (NTL(p) + NTL(p + 1)) + (NTL(p + 2) + NTL(p + 3)); ss = (a[0] + a[1]) + (a[2] + a[3]); }
;     return 1.0f / sqrtf(ss * (1.0f / DM) + EPS);
; }
; __device__ __forceinline__ void rstd_prefetch(const Frame& F, const float* PP, const float* PS) {
;     ...
;         if (ok && F.tid < 256) RSL[i * 256 + F.tid] = pg8::row_rstd(PP, PS, pm * 256 + F.tid);
.Lrs_p3_s4:
	s_sub_i32 s14, s10, 64
	v_lshl_add_u32 v1, s14, 8, v188
	v_lshlrev_b32_e32 v1, 6, v1
	global_load_dwordx4 v[84:87], v1, s[36:37]
	global_load_dwordx4 v[88:91], v1, s[36:37] offset:16
	global_load_dwordx4 v[92:95], v1, s[36:37] offset:32
	global_load_dwordx4 v[96:99], v1, s[36:37] offset:48
.Lrs_p3_l4:
	s_cmp_lt_i32 s11, 0
	s_cbranch_scc1 .Lrs_p3_l5
	s_cmp_lt_i32 s11, 64
	s_cbranch_scc0 .Lrs_p3_s5
	v_lshl_add_u32 v1, s11, 8, v188
	v_lshlrev_b32_e32 v1, 4, v1
	global_load_dwordx4 v[100:103], v1, s[16:17]
	s_branch .Lrs_p3_l5
.Lrs_p3_s5:
	s_sub_i32 s14, s11, 64
	v_lshl_add_u32 v1, s14, 8, v188
	v_lshlrev_b32_e32 v1, 6, v1
	global_load_dwordx4 v[100:103], v1, s[36:37]
	global_load_dwordx4 v[104:107], v1, s[36:37] offset:16
	global_load_dwordx4 v[108:111], v1, s[36:37] offset:32
	global_load_dwordx4 v[112:115], v1, s[36:37] offset:48
.Lrs_p3_l5:
	s_waitcnt vmcnt(0)
	s_mov_b32 s19, 0xf800000
	s_cmp_lt_i32 s6, 0
	s_cbranch_scc1 .Lrs_p3_c0
	s_cmp_lt_i32 s6, 64
	s_cbranch_scc1 .Lrs_p3_r0
	v_pk_add_f32 v[22:23], v[22:23], v[26:27]
	v_pk_add_f32 v[20:21], v[20:21], v[24:25]
	v_pk_add_f32 v[26:27], v[30:31], v[34:35]
	v_pk_add_f32 v[24:25], v[28:29], v[32:33]
	v_pk_add_f32 v[22:23], v[22:23], v[26:27]
	v_pk_add_f32 v[20:21], v[20:21], v[24:25]
.Lrs_p3_r0:
	v_add_f32_e32 v2, v21, v20
	v_add_f32_e32 v3, v22, v23
	v_add_f32_e32 v1, v2, v3
	v_mov_b32_e32 v2, 0x358637bd
	v_fmac_f32_e32 v2, 0x3a800000, v1
	v_mul_f32_e32 v1, 0x4f800000, v2
	v_cmp_gt_f32_e32 vcc, s19, v2
	s_nop 1
	v_cndmask_b32_e32 v1, v2, v1, vcc
	v_sqrt_f32_e32 v2, v1
	s_nop 0
	v_add_u32_e32 v3, -1, v2
	v_fma_f32 v4, -v3, v2, v1
	v_cmp_ge_f32_e64 s[14:15], 0, v4
	v_add_u32_e32 v4, 1, v2
	s_nop 0
	v_cndmask_b32_e64 v3, v2, v3, s[14:15]
	v_fma_f32 v2, -v4, v2, v1
	v_cmp_lt_f32_e64 s[14:15], 0, v2
	s_nop 1
	v_cndmask_b32_e64 v2, v3, v4, s[14:15]
	v_mul_f32_e32 v3, 0x37800000, v2
	v_cndmask_b32_e32 v2, v2, v3, vcc
	v_mov_b32_e32 v3, 0x260
	v_cmp_class_f32_e32 vcc, v1, v3
	s_nop 1
	v_cndmask_b32_e32 v1, v2, v1, vcc
	v_div_scale_f32 v2, s[14:15], v1, v1, 1.0
	v_rcp_f32_e32 v3, v2
	s_nop 0
	v_fma_f32 v4, -v2, v3, 1.0
	v_fmac_f32_e32 v3, v4, v3
	v_div_scale_f32 v4, vcc, 1.0, v1, 1.0
	v_mul_f32_e32 v5, v4, v3
	v_fma_f32 v6, -v2, v5, v4
	v_fmac_f32_e32 v5, v6, v3
	v_fma_f32 v2, -v2, v5, v4
	v_div_fmas_f32 v2, v2, v3, v5
	v_div_fixup_f32 v1, v2, v1, 1.0
	v_lshl_add_u32 v2, v188, 2, 0
	v_add_u32_e32 v2, 0x21000, v2
	ds_write_b32 v2, v1
.Lrs_p3_c0:
	s_cmp_lt_i32 s7, 0
	s_cbranch_scc1 .Lrs_p3_c1
	s_cmp_lt_i32 s7, 64
	s_cbranch_scc1 .Lrs_p3_r1
	v_pk_add_f32 v[38:39], v[38:39], v[42:43]
	v_pk_add_f32 v[36:37], v[36:37], v[40:41]
	v_pk_add_f32 v[42:43], v[46:47], v[50:51]
	v_pk_add_f32 v[40:41], v[44:45], v[48:49]
	v_pk_add_f32 v[38:39], v[38:39], v[42:43]
	v_pk_add_f32 v[36:37], v[36:37], v[40:41]
.Lrs_p3_r1:
	v_add_f32_e32 v2, v37, v36
	v_add_f32_e32 v3, v38, v39
	v_add_f32_e32 v1, v2, v3
	v_mov_b32_e32 v2, 0x358637bd
	v_fmac_f32_e32 v2, 0x3a800000, v1
	v_mul_f32_e32 v1, 0x4f800000, v2
	v_cmp_gt_f32_e32 vcc, s19, v2
	s_nop 1
	v_cndmask_b32_e32 v1, v2, v1, vcc
	v_sqrt_f32_e32 v2, v1
	s_nop 0
	v_add_u32_e32 v3, -1, v2
	v_fma_f32 v4, -v3, v2, v1
	v_cmp_ge_f32_e64 s[14:15], 0, v4
	v_add_u32_e32 v4, 1, v2
	s_nop 0
	v_cndmask_b32_e64 v3, v2, v3, s[14:15]
	v_fma_f32 v2, -v4, v2, v1
	v_cmp_lt_f32_e64 s[14:15], 0, v2
	s_nop 1
	v_cndmask_b32_e64 v2, v3, v4, s[14:15]
	v_mul_f32_e32 v3, 0x37800000, v2
	v_cndmask_b32_e32 v2, v2, v3, vcc
	v_mov_b32_e32 v3, 0x260
	v_cmp_class_f32_e32 vcc, v1, v3
	s_nop 1
	v_cndmask_b32_e32 v1, v2, v1, vcc
	v_div_scale_f32 v2, s[14:15], v1, v1, 1.0
	v_rcp_f32_e32 v3, v2
	s_nop 0
	v_fma_f32 v4, -v2, v3, 1.0
	v_fmac_f32_e32 v3, v4, v3
	v_div_scale_f32 v4, vcc, 1.0, v1, 1.0
	v_mul_f32_e32 v5, v4, v3
	v_fma_f32 v6, -v2, v5, v4
	v_fmac_f32_e32 v5, v6, v3
	v_fma_f32 v2, -v2, v5, v4
	v_div_fmas_f32 v2, v2, v3, v5
	v_div_fixup_f32 v1, v2, v1, 1.0
	v_lshl_add_u32 v2, v188, 2, 0
	v_add_u32_e32 v2, 0x21400, v2
	ds_write_b32 v2, v1
.Lrs_p3_c1:
	s_cmp_lt_i32 s8, 0
	s_cbranch_scc1 .Lrs_p3_c2
	s_cmp_lt_i32 s8, 64
	s_cbranch_scc1 .Lrs_p3_r2
	v_pk_add_f32 v[54:55], v[54:55], v[58:59]
	v_pk_add_f32 v[52:53], v[52:53], v[56:57]
	v_pk_add_f32 v[58:59], v[62:63], v[66:67]
	v_pk_add_f32 v[56:57], v[60:61], v[64:65]
	v_pk_add_f32 v[54:55], v[54:55], v[58:59]
	v_pk_add_f32 v[52:53], v[52:53], v[56:57]
.Lrs_p3_r2:
	v_add_f32_e32 v2, v53, v52
	v_add_f32_e32 v3, v54, v55
	v_add_f32_e32 v1, v2, v3
	v_mov_b32_e32 v2, 0x358637bd
	v_fmac_f32_e32 v2, 0x3a800000, v1
	v_mul_f32_e32 v1, 0x4f800000, v2
	v_cmp_gt_f32_e32 vcc, s19, v2
	s_nop 1
	v_cndmask_b32_e32 v1, v2, v1, vcc
	v_sqrt_f32_e32 v2, v1
	s_nop 0
	v_add_u32_e32 v3, -1, v2
	v_fma_f32 v4, -v3, v2, v1
	v_cmp_ge_f32_e64 s[14:15], 0, v4
	v_add_u32_e32 v4, 1, v2
	s_nop 0
	v_cndmask_b32_e64 v3, v2, v3, s[14:15]
	v_fma_f32 v2, -v4, v2, v1
	v_cmp_lt_f32_e64 s[14:15], 0, v2
	s_nop 1
	v_cndmask_b32_e64 v2, v3, v4, s[14:15]
	v_mul_f32_e32 v3, 0x37800000, v2
	v_cndmask_b32_e32 v2, v2, v3, vcc
	v_mov_b32_e32 v3, 0x260
	v_cmp_class_f32_e32 vcc, v1, v3
	s_nop 1
	v_cndmask_b32_e32 v1, v2, v1, vcc
	v_div_scale_f32 v2, s[14:15], v1, v1, 1.0
	v_rcp_f32_e32 v3, v2
	s_nop 0
	v_fma_f32 v4, -v2, v3, 1.0
	v_fmac_f32_e32 v3, v4, v3
	v_div_scale_f32 v4, vcc, 1.0, v1, 1.0
	v_mul_f32_e32 v5, v4, v3
	v_fma_f32 v6, -v2, v5, v4
	v_fmac_f32_e32 v5, v6, v3
	v_fma_f32 v2, -v2, v5, v4
	v_div_fmas_f32 v2, v2, v3, v5
	v_div_fixup_f32 v1, v2, v1, 1.0
	v_lshl_add_u32 v2, v188, 2, 0
	v_add_u32_e32 v2, 0x21800, v2
	ds_write_b32 v2, v1
; __device__ __forceinline__ float row_rstd(const float* PP, const float* PS, int row) {
;     float ss;
;     if (row < TP) { const f32x4 a = NTL((const f32x4*)(PP + (size_t)row * 4)); ss = (a[0] + a[1]) + (a[2] + a[3]); }
;     else { const f32x4* p = (const f32x4*)(PS + (size_t)(row - TP) * 16); const f32x4 a = (NTL(p) + NTL(p + 1)) + (NTL(p + 2) + NTL(p + 3)); ss = (a[0] + a[1]) + (a[2] + a[3]); }
;     return 1.0f / sqrtf(ss * (1.0f / DM) + EPS);
; }
; __device__ __forceinline__ void rstd_prefetch(const Frame& F, const float* PP, const float* PS) {
;     ...
;         if (ok && F.tid < 256) RSL[i * 256 + F.tid] = pg8::row_rstd(PP, PS, pm * 256 + F.tid);
;         if (F.tid == 0) PMT[i] = pm; }
;     __syncthreads();
; }
.Lrs_p3_c2:
	s_cmp_lt_i32 s9, 0
	s_cbranch_scc1 .Lrs_p3_c3
	s_cmp_lt_i32 s9, 64
	s_cbranch_scc1 .Lrs_p3_r3
	v_pk_add_f32 v[70:71], v[70:71], v[74:75]
	v_pk_add_f32 v[68:69], v[68:69], v[72:73]
	v_pk_add_f32 v[74:75], v[78:79], v[82:83]
	v_pk_add_f32 v[72:73], v[76:77], v[80:81]
	v_pk_add_f32 v[70:71], v[70:71], v[74:75]
	v_pk_add_f32 v[68:69], v[68:69], v[72:73]
.Lrs_p3_r3:
	v_add_f32_e32 v2, v69, v68
	v_add_f32_e32 v3, v70, v71
	v_add_f32_e32 v1, v2, v3
	v_mov_b32_e32 v2, 0x358637bd
	v_fmac_f32_e32 v2, 0x3a800000, v1
	v_mul_f32_e32 v1, 0x4f800000, v2
	v_cmp_gt_f32_e32 vcc, s19, v2
	s_nop 1
	v_cndmask_b32_e32 v1, v2, v1, vcc
	v_sqrt_f32_e32 v2, v1
	s_nop 0
	v_add_u32_e32 v3, -1, v2
	v_fma_f32 v4, -v3, v2, v1
	v_cmp_ge_f32_e64 s[14:15], 0, v4
	v_add_u32_e32 v4, 1, v2
	s_nop 0
	v_cndmask_b32_e64 v3, v2, v3, s[14:15]
	v_fma_f32 v2, -v4, v2, v1
	v_cmp_lt_f32_e64 s[14:15], 0, v2
	s_nop 1
	v_cndmask_b32_e64 v2, v3, v4, s[14:15]
	v_mul_f32_e32 v3, 0x37800000, v2
	v_cndmask_b32_e32 v2, v2, v3, vcc
	v_mov_b32_e32 v3, 0x260
	v_cmp_class_f32_e32 vcc, v1, v3
	s_nop 1
	v_cndmask_b32_e32 v1, v2, v1, vcc
	v_div_scale_f32 v2, s[14:15], v1, v1, 1.0
	v_rcp_f32_e32 v3, v2
	s_nop 0
	v_fma_f32 v4, -v2, v3, 1.0
	v_fmac_f32_e32 v3, v4, v3
	v_div_scale_f32 v4, vcc, 1.0, v1, 1.0
	v_mul_f32_e32 v5, v4, v3
	v_fma_f32 v6, -v2, v5, v4
	v_fmac_f32_e32 v5, v6, v3
	v_fma_f32 v2, -v2, v5, v4
	v_div_fmas_f32 v2, v2, v3, v5
	v_div_fixup_f32 v1, v2, v1, 1.0
	v_lshl_add_u32 v2, v188, 2, 0
	v_add_u32_e32 v2, 0x21c00, v2
	ds_write_b32 v2, v1
.Lrs_p3_c3:
	s_cmp_lt_i32 s10, 0
	s_cbranch_scc1 .Lrs_p3_c4
	s_cmp_lt_i32 s10, 64
	s_cbranch_scc1 .Lrs_p3_r4
	v_pk_add_f32 v[86:87], v[86:87], v[90:91]
	v_pk_add_f32 v[84:85], v[84:85], v[88:89]
	v_pk_add_f32 v[90:91], v[94:95], v[98:99]
	v_pk_add_f32 v[88:89], v[92:93], v[96:97]
	v_pk_add_f32 v[86:87], v[86:87], v[90:91]
	v_pk_add_f32 v[84:85], v[84:85], v[88:89]
.Lrs_p3_r4:
	v_add_f32_e32 v2, v85, v84
	v_add_f32_e32 v3, v86, v87
	v_add_f32_e32 v1, v2, v3
	v_mov_b32_e32 v2, 0x358637bd
	v_fmac_f32_e32 v2, 0x3a800000, v1
	v_mul_f32_e32 v1, 0x4f800000, v2
	v_cmp_gt_f32_e32 vcc, s19, v2
	s_nop 1
	v_cndmask_b32_e32 v1, v2, v1, vcc
	v_sqrt_f32_e32 v2, v1
	s_nop 0
	v_add_u32_e32 v3, -1, v2
	v_fma_f32 v4, -v3, v2, v1
	v_cmp_ge_f32_e64 s[14:15], 0, v4
	v_add_u32_e32 v4, 1, v2
	s_nop 0
	v_cndmask_b32_e64 v3, v2, v3, s[14:15]
	v_fma_f32 v2, -v4, v2, v1
	v_cmp_lt_f32_e64 s[14:15], 0, v2
	s_nop 1
	v_cndmask_b32_e64 v2, v3, v4, s[14:15]
	v_mul_f32_e32 v3, 0x37800000, v2
	v_cndmask_b32_e32 v2, v2, v3, vcc
	v_mov_b32_e32 v3, 0x260
	v_cmp_class_f32_e32 vcc, v1, v3
	s_nop 1
	v_cndmask_b32_e32 v1, v2, v1, vcc
	v_div_scale_f32 v2, s[14:15], v1, v1, 1.0
	v_rcp_f32_e32 v3, v2
	s_nop 0
	v_fma_f32 v4, -v2, v3, 1.0
	v_fmac_f32_e32 v3, v4, v3
	v_div_scale_f32 v4, vcc, 1.0, v1, 1.0
	v_mul_f32_e32 v5, v4, v3
	v_fma_f32 v6, -v2, v5, v4
	v_fmac_f32_e32 v5, v6, v3
	v_fma_f32 v2, -v2, v5, v4
	v_div_fmas_f32 v2, v2, v3, v5
	v_div_fixup_f32 v1, v2, v1, 1.0
	v_lshl_add_u32 v2, v188, 2, 0
	v_add_u32_e32 v2, 0x22000, v2
	ds_write_b32 v2, v1
.Lrs_p3_c4:
	s_cmp_lt_i32 s11, 0
	s_cbranch_scc1 .Lrs_p3_c5
	s_cmp_lt_i32 s11, 64
	s_cbranch_scc1 .Lrs_p3_r5
	v_pk_add_f32 v[102:103], v[102:103], v[106:107]
	v_pk_add_f32 v[100:101], v[100:101], v[104:105]
	v_pk_add_f32 v[106:107], v[110:111], v[114:115]
	v_pk_add_f32 v[104:105], v[108:109], v[112:113]
	v_pk_add_f32 v[102:103], v[102:103], v[106:107]
	v_pk_add_f32 v[100:101], v[100:101], v[104:105]
.Lrs_p3_r5:
	v_add_f32_e32 v2, v101, v100
	v_add_f32_e32 v3, v102, v103
	v_add_f32_e32 v1, v2, v3
	v_mov_b32_e32 v2, 0x358637bd
	v_fmac_f32_e32 v2, 0x3a800000, v1
	v_mul_f32_e32 v1, 0x4f800000, v2
	v_cmp_gt_f32_e32 vcc, s19, v2
	s_nop 1
	v_cndmask_b32_e32 v1, v2, v1, vcc
	v_sqrt_f32_e32 v2, v1
	s_nop 0
	v_add_u32_e32 v3, -1, v2
	v_fma_f32 v4, -v3, v2, v1
	v_cmp_ge_f32_e64 s[14:15], 0, v4
	v_add_u32_e32 v4, 1, v2
	s_nop 0
	v_cndmask_b32_e64 v3, v2, v3, s[14:15]
	v_fma_f32 v2, -v4, v2, v1
	v_cmp_lt_f32_e64 s[14:15], 0, v2
	s_nop 1
	v_cndmask_b32_e64 v2, v3, v4, s[14:15]
	v_mul_f32_e32 v3, 0x37800000, v2
	v_cndmask_b32_e32 v2, v2, v3, vcc
	v_mov_b32_e32 v3, 0x260
	v_cmp_class_f32_e32 vcc, v1, v3
	s_nop 1
	v_cndmask_b32_e32 v1, v2, v1, vcc
	v_div_scale_f32 v2, s[14:15], v1, v1, 1.0
	v_rcp_f32_e32 v3, v2
	s_nop 0
	v_fma_f32 v4, -v2, v3, 1.0
	v_fmac_f32_e32 v3, v4, v3
	v_div_scale_f32 v4, vcc, 1.0, v1, 1.0
	v_mul_f32_e32 v5, v4, v3
	v_fma_f32 v6, -v2, v5, v4
	v_fmac_f32_e32 v5, v6, v3
	v_fma_f32 v2, -v2, v5, v4
	v_div_fmas_f32 v2, v2, v3, v5
	v_div_fixup_f32 v1, v2, v1, 1.0
	v_lshl_add_u32 v2, v188, 2, 0
	v_add_u32_e32 v2, 0x22400, v2
	ds_write_b32 v2, v1
.Lrs_p3_c5:
.Lrs_p3_rows_done:
	s_or_b64 exec, exec, s[34:35]
	v_cmp_eq_u32_e32 vcc, 0, v188
	s_and_saveexec_b64 s[34:35], vcc
	v_mov_b32_e32 v1, 0x20c00
	v_mov_b32_e32 v2, s6
	ds_write_b32 v1, v2
	v_mov_b32_e32 v2, s7
	ds_write_b32 v1, v2 offset:4
	v_mov_b32_e32 v2, s8
	ds_write_b32 v1, v2 offset:8
	v_mov_b32_e32 v2, s9
	ds_write_b32 v1, v2 offset:12
	v_mov_b32_e32 v2, s10
	ds_write_b32 v1, v2 offset:16
	v_mov_b32_e32 v2, s11
	ds_write_b32 v1, v2 offset:20
	s_or_b64 exec, exec, s[34:35]
	v_cndmask_b32_e64 v1, 0, 1, s[12:13]
	s_mov_b64 s[14:15], s[0:1]
	v_cmp_ne_u32_e64 s[6:7], 1, v1
	s_andn2_b64 vcc, exec, s[12:13]
	v_readfirstlane_b32 s58, v0
	s_waitcnt lgkmcnt(0)
	s_barrier
	s_cbranch_vccnz .LBB0_570
	s_ashr_i32 s3, s2, 31
	s_lshr_b32 s3, s3, 29
	s_add_i32 s3, s2, s3
	s_ashr_i32 s8, s3, 3
	s_and_b32 s3, s3, -8
	s_sub_i32 s3, s2, s3
	s_cmp_lt_i32 s3, 0
	s_movk_i32 s9, 0xbc
	s_cselect_b32 s9, s9, 0xbb
	s_mul_i32 s3, s3, s9
	s_add_i32 s3, s3, s8
	s_mul_hi_i32 s8, s3, 0x2e8ba2e9
	s_lshr_b32 s9, s8, 31
	s_ashr_i32 s8, s8, 5
	s_add_i32 s8, s8, s9
	s_lshl_b32 s10, s8, 3
	s_sub_i32 s9, 0x44, s10
	s_mulk_i32 s8, 0xb0
	s_min_u32 s11, s9, 8
	s_sub_i32 s3, s3, s8
	s_sext_i32_i16 s8, s3
	v_cvt_f32_ubyte0_e32 v2, s11
	v_cvt_f32_i32_e32 v1, s8
	v_rcp_iflag_f32_e32 v3, v2
	s_ashr_i32 s8, s8, 30
	s_or_b32 s12, s8, 1
	v_mul_f32_e32 v3, v1, v3
	v_trunc_f32_e32 v3, v3
	v_fma_f32 v1, -v3, v2, v1
	v_cvt_i32_f32_e32 v3, v3
	v_cmp_ge_f32_e64 s[8:9], |v1|, v2
	s_and_b64 s[8:9], s[8:9], exec
	s_cselect_b32 s8, s12, 0
	v_readfirstlane_b32 s9, v3
	s_add_i32 s8, s9, s8
	s_sext_i32_i16 s60, s8
	s_mul_i32 s8, s8, s11
	s_sub_i32 s3, s3, s8
	s_sext_i32_i16 s3, s3
	s_add_i32 s8, s10, s3
